# P2 attention NOMAX loop: K/V stream pointer arithmetic moved from VALU (8 64-bit ops per iteration) to SALU via saddr-form LDS-DMA loads, on top of P1 LDS tables
# speedup vs baseline: 1.0307x; 1.0052x over previous
; #define WAIT_BAR(N) asm volatile("s_waitcnt vmcnt(" #N ") lgkmcnt(0)\n\ts_barrier":::"memory")
;   #define DMA_K(t,slot) glds16(ksrc+(long)(t)*KVBLK*KP,(unsigned)__builtin_amdgcn_readfirstlane(kdst+(slot)))
;   #define DMA_V(t,slot) glds16(vsrc+(long)(t)*KVBLK*KP,(unsigned)__builtin_amdgcn_readfirstlane(vdst+(slot)))
;   #define CMASK(P0,P1,t) do{}while(0)
;   #define START(P0,P1) do{ const float rm=rowmax(P0,P1); resc=false; \
;     { const float dl=rm; mhat=fadd_s(mhat,dl); \
;       _Pragma("unroll") for(int r=0;r<16;++r){P0[r]=fsub_s(P0[r],dl);P1[r]=fsub_s(P1[r],dl);} \
;       _Pragma("unroll") for(int r=0;r<16;++r)negm[r]=-mhat; asm volatile("":"+v"(negm)); } \
;     _Pragma("unroll") for(int r=0;r<16;++r)P0[r]=__builtin_amdgcn_exp2f(P0[r]); }while(0)
;   #define RESC() do{ if(resc){ asm volatile("s_waitcnt lgkmcnt(0)":::"memory"); \
;       _Pragma("unroll") for(int d_=0;d_<2;++d_) _Pragma("unroll") for(int r=0;r<16;++r)o[d_][r]*=wsf[crow(r,hi)]; } }while(0)
;   #define ROT() do{sl_prev=sl_cur;sl_cur=sl_next;sl_next=(sl_next==(NSLOT-1)*SLOTB)?0:sl_next+SLOTB;}while(0)
;   #define CMASK(P0,P1,t) do{}while(0)
;   #define CMASK(P0,P1,t) do{}while(0)
; template<int THRL,bool NOMAX> __device__ __forceinline__ void attn_unit(long rowbase,int NT,int h,int qb,const bf16*Q,const bf16*__restrict__ Kh,const bf16*__restrict__ Vh,bf16*O,char*shm,
;     bool first,bool has_next,long n_rowbase,int n_h,int n_qb,const bf16*__restrict__ n_Kh,bf16x8 (&qr)[4]){
;     ...
;   if(first){ DMA_K(2,2*SLOTB);
;   WAIT_BAR(3); }
;   else { DMA_V(0,0); WAIT_BAR(1); }
;   qkt(pA0,pA1,Kbase,qr,negm,r32,hi);asm volatile("s_nop 15\n\ts_nop 7":"+v"(pA0),"+v"(pA1));CMASK(pA0,pA1,0);
;   START(pA0,pA1);
;   _Pragma("unroll") for(int r=0;r<16;++r)pA1[r]=__builtin_amdgcn_exp2f(pA1[r]);
;   WAIT_BAR(0);
;   DMA_K(3,0);DMA_V(1,SLOTB);
;   ROT();
;   kload8(kf,kp0+sl_cur);
;   WAIT_BAR(2);
;   s16x4 vlo[8],vhi[8]; u32x4 pw0,pw1,pw2,pw3;
;     ...
;   int t=1;
;     ...
;   for(;t+5<NT;t+=2){
;     STEP(pB0,pB1,pA0,pA1,t,true,true,true);     WAIT_BAR(2); RESC(); ROT();
.LBB0_1096:
	ds_read_b128 v[50:53], v232
	s_lshl_b32 s85, s53, 3
	s_cmp_lg_u32 0x100, -1
	v_mov_b32_e32 v206, 0
	s_mov_b32 s36, 0
	v_lshl_add_u64 v[194:195], v[100:101], 0, s[16:17]
	v_lshl_add_u64 v[196:197], v[98:99], 0, s[18:19]
	s_movk_i32 s89, 0x4000
	s_movk_i32 s87, 0x2000
	s_waitcnt vmcnt(3) lgkmcnt(0)
	v_mfma_f32_32x32x16_bf16 v[34:49], v[50:53], v[130:133], v[18:33]
	ds_read_b128 v[50:53], v232 offset:512
	s_mov_b32 s6, 6
	s_mov_b32 s38, 5
	s_waitcnt lgkmcnt(0)
	v_mfma_f32_32x32x16_bf16 v[18:33], v[50:53], v[130:133], v[18:33]
	ds_read_b128 v[50:53], v232 offset:2048
	s_waitcnt vmcnt(2) lgkmcnt(0)
	v_mfma_f32_32x32x16_bf16 v[34:49], v[50:53], v[134:137], v[34:49]
	ds_read_b128 v[50:53], v232 offset:2560
	s_waitcnt lgkmcnt(0)
	v_mfma_f32_32x32x16_bf16 v[18:33], v[50:53], v[134:137], v[18:33]
	ds_read_b128 v[50:53], v232 offset:4096
	s_waitcnt vmcnt(1) lgkmcnt(0)
	v_mfma_f32_32x32x16_bf16 v[34:49], v[50:53], v[138:141], v[34:49]
	ds_read_b128 v[50:53], v232 offset:4608
	s_waitcnt lgkmcnt(0)
	v_mfma_f32_32x32x16_bf16 v[18:33], v[50:53], v[138:141], v[18:33]
	ds_read_b128 v[50:53], v232 offset:6144
	s_waitcnt vmcnt(0) lgkmcnt(0)
	v_mfma_f32_32x32x16_bf16 v[34:49], v[50:53], v[142:145], v[34:49]
	ds_read_b128 v[50:53], v232 offset:6656
	s_waitcnt lgkmcnt(0)
	v_mfma_f32_32x32x16_bf16 v[18:33], v[50:53], v[142:145], v[18:33]
	s_nop 15
	s_nop 7
	s_nop 0
	v_max3_f32 v50, v34, v35, v18
	v_max3_f32 v51, v36, v37, v19
	s_nop 0
	v_max3_f32 v50, v50, v20, v21
	v_max3_f32 v51, v51, v40, v41
	s_nop 0
	v_max3_f32 v50, v50, v38, v39
	v_max3_f32 v51, v51, v24, v25
	s_nop 0
	v_max3_f32 v50, v50, v22, v23
	v_max3_f32 v51, v51, v44, v45
	s_nop 0
	v_max3_f32 v50, v50, v42, v43
	v_max3_f32 v51, v51, v28, v29
	s_nop 0
	v_max3_f32 v50, v50, v26, v27
	v_max3_f32 v51, v51, v48, v49
	s_nop 0
	v_max3_f32 v50, v50, v46, v47
	v_max3_f32 v51, v51, v32, v33
	s_nop 0
	v_max3_f32 v50, v50, v30, v31
	s_nop 0
	v_max_f32_e32 v50, v50, v51
	s_nop 0
	v_mov_b32_e32 v51, v50
	s_nop 1
	v_permlane32_swap_b32_e32 v50, v51
	v_max_f32_e32 v50, v50, v51
	s_nop 0
	v_add_f32_e32 v51, v207, v50
	v_sub_f32_e32 v34, v34, v50
	v_sub_f32_e32 v18, v18, v50
	v_sub_f32_e32 v35, v35, v50
	v_sub_f32_e32 v19, v19, v50
	v_sub_f32_e32 v36, v36, v50
	v_sub_f32_e32 v20, v20, v50
	v_sub_f32_e32 v37, v37, v50
	v_sub_f32_e32 v21, v21, v50
	v_sub_f32_e32 v38, v38, v50
	v_sub_f32_e32 v22, v22, v50
	v_sub_f32_e32 v39, v39, v50
	v_sub_f32_e32 v23, v23, v50
	v_sub_f32_e32 v40, v40, v50
	v_sub_f32_e32 v24, v24, v50
	v_sub_f32_e32 v41, v41, v50
	v_sub_f32_e32 v25, v25, v50
	v_sub_f32_e32 v42, v42, v50
	v_sub_f32_e32 v26, v26, v50
	v_sub_f32_e32 v43, v43, v50
	v_sub_f32_e32 v27, v27, v50
	v_sub_f32_e32 v44, v44, v50
	v_sub_f32_e32 v28, v28, v50
	v_sub_f32_e32 v45, v45, v50
	v_sub_f32_e32 v29, v29, v50
	v_sub_f32_e32 v46, v46, v50
	v_sub_f32_e32 v30, v30, v50
	v_sub_f32_e32 v47, v47, v50
	v_sub_f32_e32 v31, v31, v50
	v_sub_f32_e32 v48, v48, v50
	v_sub_f32_e32 v32, v32, v50
	v_sub_f32_e32 v49, v49, v50
	v_sub_f32_e32 v33, v33, v50
	s_nop 0
	v_xor_b32_e32 v50, 0x80000000, v51
	v_mov_b32_e32 v51, v50
	v_mov_b32_e32 v52, v50
	v_mov_b32_e32 v53, v50
	v_mov_b32_e32 v54, v50
	v_mov_b32_e32 v55, v50
	v_mov_b32_e32 v56, v50
	v_mov_b32_e32 v57, v50
	v_mov_b32_e32 v58, v50
	v_mov_b32_e32 v59, v50
	v_mov_b32_e32 v60, v50
	v_mov_b32_e32 v61, v50
	v_mov_b32_e32 v62, v50
	v_mov_b32_e32 v63, v50
	v_mov_b32_e32 v64, v50
	v_mov_b32_e32 v65, v50
	s_waitcnt vmcnt(0) lgkmcnt(0)
	s_barrier
	v_exp_f32_e32 v66, v18
	v_exp_f32_e32 v67, v19
	v_lshl_add_u64 v[18:19], v[98:99], 0, s[16:17]
	s_mov_b32 s0, m0
	s_mov_b32 m0, s84
	s_nop 0
	global_load_lds_dwordx4 v[18:19], off
	s_mov_b32 m0, s0
	s_cselect_b32 s0, 0x100, 0
	s_add_i32 s0, s0, s83
	v_lshl_add_u64 v[18:19], v[100:101], 0, s[12:13]
	s_add_i32 s0, s0, 0x8000
	s_mov_b32 s1, m0
	s_mov_b32 m0, s0
	s_nop 0
	global_load_lds_dwordx4 v[18:19], off
	s_mov_b32 m0, s1
	ds_read_b128 v[190:193], v232 offset:8192
	ds_read_b128 v[186:189], v232 offset:8704
	ds_read_b128 v[182:185], v232 offset:10240
	ds_read_b128 v[178:181], v232 offset:10752
	ds_read_b128 v[174:177], v232 offset:12288
	ds_read_b128 v[170:173], v232 offset:12800
	ds_read_b128 v[166:169], v232 offset:14336
	ds_read_b128 v[162:165], v232 offset:14848
	v_exp_f32_e32 v82, v34
	v_exp_f32_e32 v83, v35
	v_exp_f32_e32 v84, v36
	v_exp_f32_e32 v85, v37
	v_exp_f32_e32 v86, v38
	v_exp_f32_e32 v87, v39
	v_exp_f32_e32 v88, v40
	v_exp_f32_e32 v89, v41
	v_exp_f32_e32 v90, v42
	v_exp_f32_e32 v91, v43
	v_exp_f32_e32 v92, v44
	v_exp_f32_e32 v93, v45
	v_exp_f32_e32 v94, v46
	v_exp_f32_e32 v95, v47
	v_exp_f32_e32 v96, v48
	v_exp_f32_e32 v97, v49
	v_exp_f32_e32 v68, v20
	v_exp_f32_e32 v69, v21
	v_exp_f32_e32 v70, v22
	v_exp_f32_e32 v71, v23
	v_exp_f32_e32 v72, v24
	v_exp_f32_e32 v73, v25
	v_exp_f32_e32 v74, v26
	v_exp_f32_e32 v75, v27
	v_exp_f32_e32 v76, v28
	v_exp_f32_e32 v77, v29
	v_exp_f32_e32 v78, v30
	v_exp_f32_e32 v79, v31
	v_exp_f32_e32 v80, v32
	v_exp_f32_e32 v81, v33
	s_waitcnt vmcnt(2) lgkmcnt(0)
	s_barrier
	v_lshl_add_u64 v[100:101], v[100:101], 0, s[20:21]
	v_lshl_add_u64 v[98:99], v[98:99], 0, s[22:23]
	v_mov_b32_e32 v18, 0
	v_mov_b32_e32 v19, v206
	v_mov_b32_e32 v20, v206
	v_mov_b32_e32 v21, v206
	v_mov_b32_e32 v22, v206
	v_mov_b32_e32 v23, v206
	v_mov_b32_e32 v24, v206
	v_mov_b32_e32 v25, v206
	v_mov_b32_e32 v26, v206
	v_mov_b32_e32 v27, v206
	v_mov_b32_e32 v28, v206
	v_mov_b32_e32 v29, v206
	v_mov_b32_e32 v30, v206
	v_mov_b32_e32 v31, v206
	v_mov_b32_e32 v32, v206
	v_mov_b32_e32 v33, v206
	v_mov_b32_e32 v34, 0
	v_mov_b32_e32 v35, v206
	v_mov_b32_e32 v36, v206
	v_mov_b32_e32 v37, v206
	v_mov_b32_e32 v38, v206
	v_mov_b32_e32 v39, v206
	v_mov_b32_e32 v40, v206
	v_mov_b32_e32 v41, v206
	v_mov_b32_e32 v42, v206
	v_mov_b32_e32 v43, v206
	v_mov_b32_e32 v44, v206
	v_mov_b32_e32 v45, v206
	v_mov_b32_e32 v46, v206
	v_mov_b32_e32 v47, v206
	v_mov_b32_e32 v48, v206
	v_mov_b32_e32 v49, v206
	v_mov_b64_e32 v[226:227], v[100:101]
	v_mov_b64_e32 v[228:229], v[98:99]
	v_subrev_u32_e32 v194, s62, v194
	v_subrev_u32_e32 v196, s62, v196
	s_mov_b64 s[100:101], s[62:63]
.LBB0_1097:
	s_mov_b32 s7, s89
	s_add_u32 s98, s100, s24
	s_mov_b32 s88, s38
	s_addc_u32 s99, s101, s25
	s_mov_b32 s37, s87
	v_add_u32_e32 v198, s36, v233
	ds_read_b64_tr_b16 v[200:201], v198 offset:24576
	ds_read_b64_tr_b16 v[202:203], v198 offset:25088
	v_add_f32_e32 v98, v82, v83
	v_add_f32_e32 v98, v84, v98
	v_add_f32_e32 v98, v85, v98
	v_add_f32_e32 v98, v86, v98
	v_add_f32_e32 v98, v87, v98
	v_cvt_pk_bf16_f32 v158, v82, v83
	v_cvt_pk_bf16_f32 v159, v84, v85
	s_waitcnt lgkmcnt(9)
	v_mfma_f32_32x32x16_bf16 v[114:129], v[190:193], v[130:133], v[50:65]
	ds_read_b64_tr_b16 v[82:83], v198 offset:28672
	ds_read_b64_tr_b16 v[84:85], v198 offset:29184
	v_add_f32_e32 v98, v88, v98
	v_add_f32_e32 v98, v89, v98
	v_add_f32_e32 v98, v90, v98
	v_add_f32_e32 v146, v91, v98
	s_waitcnt lgkmcnt(10)
	v_mfma_f32_32x32x16_bf16 v[98:113], v[186:189], v[130:133], v[50:65]
	v_cvt_pk_bf16_f32 v160, v86, v87
	v_cvt_pk_bf16_f32 v161, v88, v89
	ds_read_b64_tr_b16 v[86:87], v198 offset:25600
	ds_read_b64_tr_b16 v[88:89], v198 offset:26112
	v_add_f32_e32 v146, v92, v146
	v_add_f32_e32 v146, v93, v146
	v_add_f32_e32 v146, v94, v146
	v_add_f32_e32 v146, v95, v146
	v_cvt_pk_bf16_f32 v154, v90, v91
	v_cvt_pk_bf16_f32 v155, v92, v93
	s_waitcnt lgkmcnt(11)
	v_mfma_f32_32x32x16_bf16 v[114:129], v[182:185], v[134:137], v[114:129]
	ds_read_b64_tr_b16 v[90:91], v198 offset:29696
	ds_read_b64_tr_b16 v[92:93], v198 offset:30208
	s_waitcnt lgkmcnt(12)
	v_mfma_f32_32x32x16_bf16 v[98:113], v[178:181], v[134:137], v[98:113]
	v_add_f32_e32 v146, v96, v146
	v_add_f32_e32 v146, v97, v146
	v_add_f32_e32 v146, v66, v146
	v_add_f32_e32 v146, v67, v146
	v_cvt_pk_bf16_f32 v156, v94, v95
	v_cvt_pk_bf16_f32 v157, v96, v97
	ds_read_b64_tr_b16 v[94:95], v198 offset:26624
	ds_read_b64_tr_b16 v[96:97], v198 offset:27136
	v_add_f32_e32 v146, v68, v146
	v_add_f32_e32 v146, v69, v146
	v_add_f32_e32 v146, v70, v146
	v_add_f32_e32 v146, v71, v146
	v_cvt_pk_bf16_f32 v150, v66, v67
	v_cvt_pk_bf16_f32 v151, v68, v69
	s_waitcnt lgkmcnt(13)
	v_mfma_f32_32x32x16_bf16 v[114:129], v[174:177], v[138:141], v[114:129]
	ds_read_b64_tr_b16 v[66:67], v198 offset:30720
	ds_read_b64_tr_b16 v[68:69], v198 offset:31232
	s_waitcnt lgkmcnt(14)
	v_mfma_f32_32x32x16_bf16 v[98:113], v[170:173], v[138:141], v[98:113]
	v_add_f32_e32 v146, v72, v146
	v_add_f32_e32 v146, v73, v146
	v_add_f32_e32 v146, v74, v146
	v_add_f32_e32 v146, v75, v146
	v_cvt_pk_bf16_f32 v152, v70, v71
	v_cvt_pk_bf16_f32 v153, v72, v73
	ds_read_b64_tr_b16 v[70:71], v198 offset:27648
	ds_read_b64_tr_b16 v[72:73], v198 offset:28160
	v_add_f32_e32 v146, v76, v146
	v_add_f32_e32 v146, v77, v146
	v_add_f32_e32 v146, v78, v146
	v_add_f32_e32 v170, v79, v146
	v_cvt_pk_bf16_f32 v146, v74, v75
	v_cvt_pk_bf16_f32 v147, v76, v77
	s_waitcnt lgkmcnt(14)
	v_mfma_f32_32x32x16_bf16 v[114:129], v[166:169], v[142:145], v[114:129]
	ds_read_b64_tr_b16 v[74:75], v198 offset:31744
	ds_read_b64_tr_b16 v[76:77], v198 offset:32256
	v_mfma_f32_32x32x16_bf16 v[98:113], v[162:165], v[142:145], v[98:113]
	v_add_f32_e32 v148, v80, v170
	v_add_f32_e32 v148, v81, v148
	v_add_f32_e32 v198, 0, v148
	v_cvt_pk_bf16_f32 v148, v78, v79
	v_cvt_pk_bf16_f32 v149, v80, v81
	s_add_i32 s0, s87, s84
	s_mov_b32 s1, m0
	s_mov_b32 m0, s0
	s_nop 0
	global_load_lds_dwordx4 v196, s[98:99]
	s_mov_b32 m0, s1
	s_add_i32 s0, s89, s8
	s_mov_b32 s1, m0
	s_mov_b32 m0, s0
	s_nop 0
	global_load_lds_dwordx4 v194, s[98:99]
	s_mov_b32 m0, s1
	s_waitcnt lgkmcnt(14)
	v_mfma_f32_32x32x16_bf16 v[18:33], v[158:161], v[200:203], v[18:33]
	v_exp_f32_e32 v114, v114
	v_exp_f32_e32 v115, v115
	v_exp_f32_e32 v116, v116
	v_exp_f32_e32 v117, v117
	s_waitcnt lgkmcnt(12)
	v_mfma_f32_32x32x16_bf16 v[34:49], v[158:161], v[82:85], v[34:49]
	v_exp_f32_e32 v118, v118
	v_exp_f32_e32 v119, v119
	v_exp_f32_e32 v120, v120
	v_exp_f32_e32 v121, v121
	v_add_u32_e32 v82, s7, v232
	ds_read_b128 v[78:81], v82
	ds_read_b128 v[162:165], v82 offset:512
	s_waitcnt lgkmcnt(12)
	v_mfma_f32_32x32x16_bf16 v[18:33], v[154:157], v[86:89], v[18:33]
	v_exp_f32_e32 v122, v122
	v_exp_f32_e32 v123, v123
	v_exp_f32_e32 v124, v124
	v_exp_f32_e32 v125, v125
	ds_read_b128 v[166:169], v82 offset:2048
	ds_read_b128 v[170:173], v82 offset:2560
	s_waitcnt lgkmcnt(12)
	v_mfma_f32_32x32x16_bf16 v[34:49], v[154:157], v[90:93], v[34:49]
	v_exp_f32_e32 v126, v126
	v_exp_f32_e32 v127, v127
	v_exp_f32_e32 v128, v128
	v_exp_f32_e32 v129, v129
	ds_read_b128 v[174:177], v82 offset:4096
	ds_read_b128 v[178:181], v82 offset:4608
	s_waitcnt lgkmcnt(12)
	v_mfma_f32_32x32x16_bf16 v[18:33], v[150:153], v[94:97], v[18:33]
	v_exp_f32_e32 v98, v98
	v_exp_f32_e32 v99, v99
	v_exp_f32_e32 v100, v100
	v_exp_f32_e32 v101, v101
	ds_read_b128 v[182:185], v82 offset:6144
	ds_read_b128 v[186:189], v82 offset:6656
	s_waitcnt lgkmcnt(12)
	v_mfma_f32_32x32x16_bf16 v[34:49], v[150:153], v[66:69], v[34:49]
	v_exp_f32_e32 v102, v102
	v_exp_f32_e32 v103, v103
	v_exp_f32_e32 v104, v104
	v_exp_f32_e32 v105, v105
	s_waitcnt lgkmcnt(10)
	v_mfma_f32_32x32x16_bf16 v[18:33], v[146:149], v[70:73], v[18:33]
	v_exp_f32_e32 v106, v106
	v_exp_f32_e32 v107, v107
	v_exp_f32_e32 v108, v108
	v_exp_f32_e32 v109, v109
	s_waitcnt lgkmcnt(8)
	v_mfma_f32_32x32x16_bf16 v[34:49], v[146:149], v[74:77], v[34:49]
	v_exp_f32_e32 v110, v110
	v_exp_f32_e32 v111, v111
	v_exp_f32_e32 v112, v112
	v_exp_f32_e32 v113, v113
	s_waitcnt vmcnt(2) lgkmcnt(0)
	s_barrier
; #define WAIT_BAR(N) asm volatile("s_waitcnt vmcnt(" #N ") lgkmcnt(0)\n\ts_barrier":::"memory")
;   #define RESC() do{ if(resc){ asm volatile("s_waitcnt lgkmcnt(0)":::"memory"); \
;       _Pragma("unroll") for(int d_=0;d_<2;++d_) _Pragma("unroll") for(int r=0;r<16;++r)o[d_][r]*=wsf[crow(r,hi)]; } }while(0)
;   #define ROT() do{sl_prev=sl_cur;sl_cur=sl_next;sl_next=(sl_next==(NSLOT-1)*SLOTB)?0:sl_next+SLOTB;}while(0)
; template<int THRL,bool NOMAX> __device__ __forceinline__ void attn_unit(long rowbase,int NT,int h,int qb,const bf16*Q,const bf16*__restrict__ Kh,const bf16*__restrict__ Vh,bf16*O,char*shm,
;     bool first,bool has_next,long n_rowbase,int n_h,int n_qb,const bf16*__restrict__ n_Kh,bf16x8 (&qr)[4]){
;     ...
;   int t=1;
;     ...
;   for(;t+5<NT;t+=2){
;     STEP(pB0,pB1,pA0,pA1,t,true,true,true);     WAIT_BAR(2); RESC(); ROT();
;     STEP(pA0,pA1,pB0,pB1,t+1,true,true,true);   WAIT_BAR(2); RESC(); ROT();
	s_add_i32 s0, s89, 0x2000
	s_cmpk_lg_i32 s89, 0x4000
	s_cselect_b32 s87, s0, 0
	v_add_u32_e32 v199, s37, v233
	ds_read_b64_tr_b16 v[190:191], v199 offset:24576
	ds_read_b64_tr_b16 v[192:193], v199 offset:25088
	s_waitcnt lgkmcnt(9)
	v_mfma_f32_32x32x16_bf16 v[82:97], v[78:81], v[130:133], v[50:65]
	v_add_f32_e32 v66, v114, v115
	v_add_f32_e32 v66, v116, v66
	v_add_f32_e32 v66, v117, v66
	v_add_f32_e32 v66, v118, v66
	v_add_f32_e32 v66, v119, v66
	v_cvt_pk_bf16_f32 v158, v114, v115
	v_cvt_pk_bf16_f32 v159, v116, v117
	ds_read_b64_tr_b16 v[114:115], v199 offset:28672
	ds_read_b64_tr_b16 v[116:117], v199 offset:29184
	v_add_f32_e32 v66, v120, v66
	v_add_f32_e32 v66, v121, v66
	v_add_f32_e32 v66, v122, v66
	v_add_f32_e32 v146, v123, v66
	s_waitcnt lgkmcnt(10)
	v_mfma_f32_32x32x16_bf16 v[66:81], v[162:165], v[130:133], v[50:65]
	v_cvt_pk_bf16_f32 v160, v118, v119
	v_cvt_pk_bf16_f32 v161, v120, v121
	ds_read_b64_tr_b16 v[118:119], v199 offset:25600
	ds_read_b64_tr_b16 v[120:121], v199 offset:26112
	s_waitcnt lgkmcnt(11)
	v_mfma_f32_32x32x16_bf16 v[82:97], v[166:169], v[134:137], v[82:97]
	v_add_f32_e32 v146, v124, v146
	v_add_f32_e32 v146, v125, v146
	v_add_f32_e32 v146, v126, v146
	v_add_f32_e32 v146, v127, v146
	v_cvt_pk_bf16_f32 v154, v122, v123
	v_cvt_pk_bf16_f32 v155, v124, v125
	ds_read_b64_tr_b16 v[122:123], v199 offset:29696
	ds_read_b64_tr_b16 v[124:125], v199 offset:30208
	s_waitcnt lgkmcnt(12)
	v_mfma_f32_32x32x16_bf16 v[66:81], v[170:173], v[134:137], v[66:81]
	v_add_f32_e32 v146, v128, v146
	v_add_f32_e32 v146, v129, v146
	v_add_f32_e32 v146, v98, v146
	v_add_f32_e32 v146, v99, v146
	v_cvt_pk_bf16_f32 v156, v126, v127
	v_cvt_pk_bf16_f32 v157, v128, v129
	ds_read_b64_tr_b16 v[126:127], v199 offset:26624
	ds_read_b64_tr_b16 v[128:129], v199 offset:27136
	s_waitcnt lgkmcnt(13)
	v_mfma_f32_32x32x16_bf16 v[82:97], v[174:177], v[138:141], v[82:97]
	v_add_f32_e32 v146, v100, v146
	v_add_f32_e32 v146, v101, v146
	v_add_f32_e32 v146, v102, v146
	v_add_f32_e32 v146, v103, v146
	v_cvt_pk_bf16_f32 v150, v98, v99
	v_cvt_pk_bf16_f32 v151, v100, v101
	ds_read_b64_tr_b16 v[98:99], v199 offset:30720
	ds_read_b64_tr_b16 v[100:101], v199 offset:31232
	s_waitcnt lgkmcnt(14)
	v_mfma_f32_32x32x16_bf16 v[66:81], v[178:181], v[138:141], v[66:81]
	v_add_f32_e32 v146, v104, v146
	v_add_f32_e32 v146, v105, v146
	v_add_f32_e32 v146, v106, v146
	v_add_f32_e32 v146, v107, v146
	v_cvt_pk_bf16_f32 v152, v102, v103
	v_cvt_pk_bf16_f32 v153, v104, v105
	ds_read_b64_tr_b16 v[102:103], v199 offset:27648
	ds_read_b64_tr_b16 v[104:105], v199 offset:28160
	s_waitcnt lgkmcnt(14)
	v_mfma_f32_32x32x16_bf16 v[82:97], v[182:185], v[142:145], v[82:97]
	v_add_f32_e32 v146, v108, v146
	v_add_f32_e32 v146, v109, v146
	v_add_f32_e32 v146, v110, v146
	v_add_f32_e32 v162, v111, v146
	v_cvt_pk_bf16_f32 v146, v106, v107
	v_cvt_pk_bf16_f32 v147, v108, v109
	ds_read_b64_tr_b16 v[106:107], v199 offset:31744
	ds_read_b64_tr_b16 v[108:109], v199 offset:32256
	v_mfma_f32_32x32x16_bf16 v[66:81], v[186:189], v[142:145], v[66:81]
	v_add_f32_e32 v148, v112, v162
	v_add_f32_e32 v148, v113, v148
	v_add_f32_e32 v199, 0, v148
	v_cvt_pk_bf16_f32 v148, v110, v111
	v_cvt_pk_bf16_f32 v149, v112, v113
	s_add_i32 s0, s89, s84
	s_mov_b32 s1, m0
	s_mov_b32 m0, s0
	s_nop 0
	global_load_lds_dwordx4 v196, s[100:101]
	s_mov_b32 m0, s1
	s_add_i32 s0, s87, s8
	s_mov_b32 s1, m0
	s_mov_b32 m0, s0
	s_nop 0
	global_load_lds_dwordx4 v194, s[100:101]
	s_mov_b32 m0, s1
	s_waitcnt lgkmcnt(14)
	v_mfma_f32_32x32x16_bf16 v[18:33], v[158:161], v[190:193], v[18:33]
	v_exp_f32_e32 v82, v82
	v_exp_f32_e32 v83, v83
	v_exp_f32_e32 v84, v84
	v_exp_f32_e32 v85, v85
	s_waitcnt lgkmcnt(12)
	v_mfma_f32_32x32x16_bf16 v[34:49], v[158:161], v[114:117], v[34:49]
	v_exp_f32_e32 v86, v86
	v_exp_f32_e32 v87, v87
	v_exp_f32_e32 v88, v88
	v_exp_f32_e32 v89, v89
	v_add_u32_e32 v110, s87, v232
	ds_read_b128 v[190:193], v110
	ds_read_b128 v[186:189], v110 offset:512
	s_waitcnt lgkmcnt(12)
	v_mfma_f32_32x32x16_bf16 v[18:33], v[154:157], v[118:121], v[18:33]
	v_exp_f32_e32 v90, v90
	v_exp_f32_e32 v91, v91
	v_exp_f32_e32 v92, v92
	v_exp_f32_e32 v93, v93
	ds_read_b128 v[182:185], v110 offset:2048
	ds_read_b128 v[178:181], v110 offset:2560
	s_waitcnt lgkmcnt(12)
	v_mfma_f32_32x32x16_bf16 v[34:49], v[154:157], v[122:125], v[34:49]
	v_exp_f32_e32 v94, v94
	v_exp_f32_e32 v95, v95
	v_exp_f32_e32 v96, v96
	v_exp_f32_e32 v97, v97
	ds_read_b128 v[174:177], v110 offset:4096
	ds_read_b128 v[170:173], v110 offset:4608
	s_waitcnt lgkmcnt(12)
	v_mfma_f32_32x32x16_bf16 v[18:33], v[150:153], v[126:129], v[18:33]
	v_exp_f32_e32 v66, v66
	v_exp_f32_e32 v67, v67
	v_exp_f32_e32 v68, v68
	v_exp_f32_e32 v69, v69
	ds_read_b128 v[166:169], v110 offset:6144
	ds_read_b128 v[162:165], v110 offset:6656
	s_waitcnt lgkmcnt(12)
	v_mfma_f32_32x32x16_bf16 v[34:49], v[150:153], v[98:101], v[34:49]
	v_exp_f32_e32 v70, v70
	v_exp_f32_e32 v71, v71
	v_exp_f32_e32 v72, v72
	v_exp_f32_e32 v73, v73
	s_waitcnt lgkmcnt(10)
	v_mfma_f32_32x32x16_bf16 v[18:33], v[146:149], v[102:105], v[18:33]
	v_exp_f32_e32 v74, v74
	v_exp_f32_e32 v75, v75
	v_exp_f32_e32 v76, v76
	v_exp_f32_e32 v77, v77
	s_waitcnt lgkmcnt(8)
	v_mfma_f32_32x32x16_bf16 v[34:49], v[146:149], v[106:109], v[34:49]
	v_exp_f32_e32 v78, v78
	v_exp_f32_e32 v79, v79
	v_exp_f32_e32 v80, v80
	v_exp_f32_e32 v81, v81
	s_add_i32 s0, s87, 0x2000
	s_waitcnt vmcnt(2) lgkmcnt(0)
	s_barrier
	s_cmpk_lg_i32 s87, 0x4000
	v_add_f32_e32 v102, v206, v198
	s_mov_b32 s36, s89
	s_cselect_b32 s89, s0, 0
	s_add_i32 s6, s6, 2
	s_add_i32 s38, s38, 2
	s_add_u32 s100, s100, s14
	s_addc_u32 s101, s101, s15
	s_cmp_ge_u32 s6, s82
	v_add_f32_e32 v206, v102, v199
	s_cbranch_scc0 .LBB0_1097
	s_sub_u32 s98, s100, s62
	s_subb_u32 s99, s101, s63
	s_sub_u32 s98, s98, s14
	s_subb_u32 s99, s99, s15
	v_lshl_add_u64 v[226:227], v[226:227], 0, s[98:99]
	v_lshl_add_u64 v[228:229], v[228:229], 0, s[98:99]
	s_add_i32 s0, s6, -4
	s_cmp_ge_u32 s0, s82
	s_cbranch_scc1 .LBB0_1132
	s_add_i32 s90, s6, -5
